# phase B work distribution: the shortest attention item of each workgroup 0-127 (which also runs a compression GEMM item) is run by workgroup +128 as a fifth item
# baseline (speedup 1.0000x reference)
; DI int my_tid() { int t = threadIdx.x; asm volatile("" : "+v"(t)); return t; }
; DI Params relaunder(const Params& p0) { Params p = p0; size_t z = 0; asm volatile("" : "+s"(z)); p.ws = p0.ws + z; return p; }
; DI void phaseB(const Params& p0, int layer, unsigned char* lds, bool probe) {
;     ...
;   for (int it = blockIdx.x; it < NITEM; it += gridDim.x) {
;     const Params p = relaunder(p0);
;     if (it < 128) { compress_partial(p, it, lds); continue; }
;     const int i = it - 128, qt = 7 - (i >> 7), bh = i & 127;
;     sb_attn_wave(p, bh >> 3, bh & 7, qt * 256 + (my_tid() >> 6) * 32, probe ? p.dummy() : p.sbz());
.LBB0_550:
	v_readlane_b32 s4, v254, 45
	s_add_i32 s17, s17, s94
	s_add_i32 s16, s16, s4
	s_add_i32 s1, s1, s94
	s_cmpk_lt_i32 s17, 0x400
	s_cbranch_scc1 .LBB0_551
	s_cmpk_lt_i32 s17, 0x480
	s_cbranch_scc1 .LBB0_547
	s_cmpk_lt_i32 s17, 0x500
	s_cbranch_scc0 .LBB0_547
	s_addk_i32 s17, 0xff80
	s_addk_i32 s1, 0xff80
	s_addk_i32 s16, 0xff00
